# speedup vs baseline: 1.0112x; 1.0012x over previous
; template <int KS, bool SAFE> __device__ __forceinline__ void fused_ks(f32x16* o, f32x16& lacc, int vb, const VFrag& cur, VFrag& nxt, f32x16& p0, f32x16& p1, float& ps, ...
;   if constexpr (KS < 3) { vfrag_issue<KS + 1>(nxt, vb); asm volatile("s_waitcnt lgkmcnt(8)" ::: "memory"); }
;   else asm volatile("s_waitcnt lgkmcnt(0)" ::: "memory");
;   const bf16x8 pa = (KS == 0) ? pa0 : (KS == 1) ? pa1 : (KS == 2) ? pa2 : pa3;
;   SBAR();
;   o[0] = MFMA32(pa, PKV(cur.l0, cur.h0), o[0]); SBAR(); sm1_chunk<KS * 4 + 0>(p0, p1); if constexpr (KS > 0) SM2_UNIT(2 * KS - 1); SBAR();
;   o[1] = MFMA32(pa, PKV(cur.l1, cur.h1), o[1]); SBAR(); sm1_chunk<KS * 4 + 1>(p0, p1);
;   if (dow) {
;     if constexpr (KS == 0) { asm volatile("s_waitcnt vmcnt(0)" ::: "memory"); *reinterpret_cast<bf16x8*>(sd.k0) = st.ks0; }
;     else if constexpr (KS == 1) *reinterpret_cast<bf16x8*>(sd.k1) = st.ks1;
;     else if constexpr (KS == 2) *reinterpret_cast<bf16x8*>(sd.v0) = st.vs0;
;     else *reinterpret_cast<bf16x8*>(sd.v1) = st.vs1;
;   }
;   SBAR();
;   o[2] = MFMA32(pa, PKV(cur.l2, cur.h2), o[2]); SBAR(); sm1_chunk<KS * 4 + 2>(p0, p1); SM2_UNIT(2 * KS); SBAR();
;   o[3] = MFMA32(pa, PKV(cur.l3, cur.h3), o[3]); SBAR(); sm1_chunk<KS * 4 + 3>(p0, p1); SBAR();
;   if constexpr (!SAFE) { lacc = MFMA32(pa, ones, lacc); SBAR(); }
; }
; template <bool SAFE> ...
;   bf16x8 kb[8];
; #pragma unroll
;   for (int d0 = 0; d0 < 4; ++d0) { const int cb = (cb0 + d0 * 16 + hi * 8) * 2;
;     kb[2 * d0] = *reinterpret_cast<const bf16x8*>((const char*)Ks + KSWZ(r32, cb));
;     kb[2 * d0 + 1] = *reinterpret_cast<const bf16x8*>((const char*)Ks + KSWZ(32 + r32, cb)); }
;   VFrag fa, fb;
;   vfrag_issue<0>(fa, vb);
;   p0 = MFMA32(kb[0], qr[0], cinit); p1 = MFMA32(kb[1], qr[0], cinit);
; #pragma unroll
;   for (int d0 = 1; d0 < 4; ++d0) { p0 = MFMA32(kb[2 * d0], qr[d0], p0); p1 = MFMA32(kb[2 * d0 + 1], qr[d0], p1); }
;   SBAR();
;   unsigned a0, a1, b0, b1; ps = 0.f;
;   fused_ks<0, SAFE>(o, lacc, vb, fa, fb, p0, p1, ps, a0, a1, b0, b1, pa0, pa1, pa2, pa3, st, sd, dow, ones);
;   fused_ks<1, SAFE>(o, lacc, vb, fb, fa, p0, p1, ps, a0, a1, b0, b1, pa0, pa1, pa2, pa3, st, sd, dow, ones);
;   fused_ks<2, SAFE>(o, lacc, vb, fa, fb, p0, p1, ps, a0, a1, b0, b1, pa0, pa1, pa2, pa3, st, sd, dow, ones);
;   fused_ks<3, SAFE>(o, lacc, vb, fb, fa, p0, p1, ps, a0, a1, b0, b1, pa0, pa1, pa2, pa3, st, sd, dow, ones);
.LBB0_105:
	ds_read_b128 v[212:215], v77 offset:49152
	ds_read_b128 v[216:219], v77 offset:57344
	s_lshl_b32 s7, s6, 14
	s_add_i32 s66, s7, 0
	s_add_i32 s98, s5, 2
	s_min_i32 s98, s98, s93
	s_mul_i32 s98, s98, 0x60000
	s_add_u32 s98, s10, s98
	s_addc_u32 s99, s11, 0
	s_add_u32 s100, s98, 0x30000
	s_addc_u32 s101, s99, 0
	v_add_u32_e32 v173, s66, v209
	v_mov_b32_e32 v176, v180
	v_mfma_f32_32x32x16_bf16 v[112:127], v[68:71], v[132:135], v[80:95]
	v_mov_b32_e32 v180, v160
	v_add_u32_e32 v160, s66, v210
	v_lshl_add_u32 v194, s4, 14, v211
	s_mov_b32 s8, s9
	s_lshl_b32 s9, s9, 14
	s_add_i32 s9, s9, 0
	v_add_u32_e32 v76, s9, v207
	v_mov_b32_e32 v184, v170
	v_mfma_f32_32x32x16_bf16 v[96:111], v[72:75], v[132:135], v[80:95]
	ds_read_b128 v[68:71], v173 offset:49152
	ds_read_b128 v[72:75], v173 offset:57344
	v_mov_b32_e32 v177, v181
	v_mov_b32_e32 v172, v188
	v_mov_b32_e32 v181, v161
	v_add_u32_e32 v188, s9, v205
	v_add_u32_e32 v161, s9, v203
	v_add_u32_e32 v170, s9, v204
	s_waitcnt lgkmcnt(3)
	v_mfma_f32_32x32x16_bf16 v[112:127], v[212:215], v[136:139], v[112:127]
	ds_read_b128 v[212:215], v160 offset:49152
	v_mov_b32_e32 v185, v171
	s_waitcnt lgkmcnt(3)
	v_mfma_f32_32x32x16_bf16 v[96:111], v[216:219], v[136:139], v[96:111]
	ds_read_b128 v[216:219], v160 offset:57344
	v_mov_b32_e32 v173, v189
	v_add_u32_e32 v189, s9, v206
	v_add_u32_e32 v77, s9, v208
	s_waitcnt lgkmcnt(3)
	v_mfma_f32_32x32x16_bf16 v[112:127], v[68:71], v[140:143], v[112:127]
	ds_read_b64_tr_b16 v[220:221], v194 offset:0
	ds_read_b64_tr_b16 v[222:223], v194 offset:0x800
	s_waitcnt lgkmcnt(4)
	v_mfma_f32_32x32x16_bf16 v[96:111], v[72:75], v[140:143], v[96:111]
	s_waitcnt lgkmcnt(3)
	v_mfma_f32_32x32x16_bf16 v[112:127], v[212:215], v[144:147], v[112:127]
	ds_read_b64_tr_b16 v[212:213], v194 offset:0x200
	ds_read_b64_tr_b16 v[214:215], v194 offset:0xa00
	ds_read_b64_tr_b16 v[224:225], v194 offset:0x400
	ds_read_b64_tr_b16 v[226:227], v194 offset:0xc00
	ds_read_b64_tr_b16 v[228:229], v194 offset:0x600
	ds_read_b64_tr_b16 v[230:231], v194 offset:0xe00
	s_waitcnt lgkmcnt(7)
	v_mfma_f32_32x32x16_bf16 v[96:111], v[216:219], v[144:147], v[96:111]
	ds_read_b64_tr_b16 v[216:217], v194 offset:0x1000
	ds_read_b64_tr_b16 v[218:219], v194 offset:0x1800
	ds_read_b64_tr_b16 v[232:233], v194 offset:0x1200
	ds_read_b64_tr_b16 v[234:235], v194 offset:0x1a00
	ds_read_b64_tr_b16 v[236:237], v194 offset:0x1400
	ds_read_b64_tr_b16 v[238:239], v194 offset:0x1c00
	ds_read_b64_tr_b16 v[240:241], v194 offset:0x1600
	ds_read_b64_tr_b16 v[242:243], v194 offset:0x1e00
	s_waitcnt lgkmcnt(8)
	v_mfma_f32_32x32x16_bf16 v[48:63], v[180:183], v[220:223], v[48:63]
	s_nop 0
	v_exp_f32_e32 v112, v112
	v_exp_f32_e32 v113, v113
	v_mfma_f32_32x32x16_bf16 v[32:47], v[180:183], v[212:215], v[32:47]
	v_exp_f32_e32 v114, v114
	v_exp_f32_e32 v115, v115
	s_waitcnt vmcnt(3)
	ds_write_b128 v161, v[166:169] offset:49152
	global_load_dwordx4 v[166:169], v247, s[98:99] offset:1024
	v_mfma_f32_32x32x16_bf16 v[0:15], v[180:183], v[224:227], v[0:15]
	v_exp_f32_e32 v171, v116
	v_cvt_pk_bf16_f32 v160, v112, v113
	v_cvt_pk_bf16_f32 v161, v114, v115
	v_exp_f32_e32 v220, v117
	v_mfma_f32_32x32x16_bf16 v[16:31], v[180:183], v[228:231], v[16:31]
	v_exp_f32_e32 v221, v118
	v_exp_f32_e32 v222, v119
	v_mfma_f32_16x16x32_bf16 v[64:67], v[180:183], v[148:151], v[64:67]
	ds_read_b64_tr_b16 v[112:113], v194 offset:0x2000
	ds_read_b64_tr_b16 v[114:115], v194 offset:0x2800
	ds_read_b64_tr_b16 v[116:117], v194 offset:0x2200
	ds_read_b64_tr_b16 v[118:119], v194 offset:0x2a00
	ds_read_b64_tr_b16 v[248:249], v194 offset:0x2400
	ds_read_b64_tr_b16 v[250:251], v194 offset:0x2c00
	ds_read_b64_tr_b16 v[212:213], v194 offset:0x2600
	ds_read_b64_tr_b16 v[214:215], v194 offset:0x2e00
	s_waitcnt lgkmcnt(8)
	v_mfma_f32_32x32x16_bf16 v[48:63], v[184:187], v[216:219], v[48:63]
	v_cvt_pk_bf16_f32 v182, v171, v220
	v_cvt_pk_bf16_f32 v183, v221, v222
	v_exp_f32_e32 v120, v120
	v_exp_f32_e32 v121, v121
	v_mfma_f32_32x32x16_bf16 v[32:47], v[184:187], v[232:235], v[32:47]
	v_exp_f32_e32 v122, v122
	v_exp_f32_e32 v123, v123
	s_waitcnt vmcnt(3)
	ds_write_b128 v170, v[162:165] offset:49152
	global_load_dwordx4 v[162:165], v247, s[100:101] offset:1024
	v_mfma_f32_32x32x16_bf16 v[0:15], v[184:187], v[236:239], v[0:15]
	v_exp_f32_e32 v180, v124
	v_exp_f32_e32 v181, v125
	v_cvt_pk_bf16_f32 v170, v120, v121
	v_cvt_pk_bf16_f32 v171, v122, v123
	v_mfma_f32_32x32x16_bf16 v[16:31], v[184:187], v[240:243], v[16:31]
	v_exp_f32_e32 v220, v126
	v_exp_f32_e32 v221, v127
	v_mfma_f32_16x16x32_bf16 v[64:67], v[184:187], v[148:151], v[64:67]
	s_waitcnt lgkmcnt(0)
	s_barrier
; #define SBAR() __builtin_amdgcn_sched_barrier(0)
; template <int KS, bool SAFE> __device__ __forceinline__ void fused_ks(f32x16* o, f32x16& lacc, int vb, const VFrag& cur, VFrag& nxt, f32x16& p0, f32x16& p1, float& ps, ...
;   if constexpr (KS < 3) { vfrag_issue<KS + 1>(nxt, vb); asm volatile("s_waitcnt lgkmcnt(8)" ::: "memory"); }
;   else asm volatile("s_waitcnt lgkmcnt(0)" ::: "memory");
;   const bf16x8 pa = (KS == 0) ? pa0 : (KS == 1) ? pa1 : (KS == 2) ? pa2 : pa3;
;   SBAR();
;   o[0] = MFMA32(pa, PKV(cur.l0, cur.h0), o[0]); SBAR(); sm1_chunk<KS * 4 + 0>(p0, p1); if constexpr (KS > 0) SM2_UNIT(2 * KS - 1); SBAR();
;   o[1] = MFMA32(pa, PKV(cur.l1, cur.h1), o[1]); SBAR(); sm1_chunk<KS * 4 + 1>(p0, p1);
;   if (dow) {
;     if constexpr (KS == 0) { asm volatile("s_waitcnt vmcnt(0)" ::: "memory"); *reinterpret_cast<bf16x8*>(sd.k0) = st.ks0; }
;     else if constexpr (KS == 1) *reinterpret_cast<bf16x8*>(sd.k1) = st.ks1;
;     else if constexpr (KS == 2) *reinterpret_cast<bf16x8*>(sd.v0) = st.vs0;
;     else *reinterpret_cast<bf16x8*>(sd.v1) = st.vs1;
;   }
;   SBAR();
;   o[2] = MFMA32(pa, PKV(cur.l2, cur.h2), o[2]); SBAR(); sm1_chunk<KS * 4 + 2>(p0, p1); SM2_UNIT(2 * KS); SBAR();
;   o[3] = MFMA32(pa, PKV(cur.l3, cur.h3), o[3]); SBAR(); sm1_chunk<KS * 4 + 3>(p0, p1); SBAR();
;   if constexpr (!SAFE) { lacc = MFMA32(pa, ones, lacc); SBAR(); }
; }
; template <bool SAFE>
; __device__ __forceinline__ void diff_core(const bf16* __restrict__ Kh, const bf16* __restrict__ Vh, const int NT, const bf16x8* qr, char* lds,
;                                           const int wid, const int lane_unused, f32x16* o, f32x16& lacc, float& l_reg) {
;     ...
;   for (int j = 1; j < NT; ++j) {
;     const bool dow = true;
;     const bf16* Kc = (const bf16*)((const char*)K_lds + bc * SHM_K);
;     StgDst sd;
;     sd.v0 = (char*)V_lds + bn * SHM_V + vst0; sd.v1 = (char*)V_lds + bn * SHM_V + vst1;
;     sd.k0 = (char*)K_lds + bn * SHM_K + kw0;  sd.k1 = (char*)K_lds + bn * SHM_K + kw1;
;     tile_step<SAFE>(o, lacc, Kc, vb0 + bp * SHM_V, qr, rk, hi, cb0, p0, p1, cinit, ps, pa0, pa1, pa2, pa3, sr_[0], sd, dow, ones);
;     SLOAD(0, min(j + 2, NT - 1) * 64);
;     SBAR();
;     if constexpr (SAFE) FIXUP(Kc, false);
;     asm volatile("s_waitcnt lgkmcnt(0)" ::: "memory"); __builtin_amdgcn_s_barrier(); asm volatile("" ::: "memory");
;     const int t_ = bp; bp = bc; bc = bn; bn = t_;
	v_mfma_f32_32x32x16_bf16 v[48:63], v[176:179], v[112:115], v[48:63]
	ds_read_b128 v[68:71], v76 offset:49152
	ds_read_b128 v[72:75], v76 offset:57344
	ds_read_b64_tr_b16 v[120:121], v194 offset:0x3000
	ds_read_b64_tr_b16 v[122:123], v194 offset:0x3800
	ds_read_b64_tr_b16 v[124:125], v194 offset:0x3200
	ds_read_b64_tr_b16 v[126:127], v194 offset:0x3a00
	ds_read_b64_tr_b16 v[252:253], v194 offset:0x3400
	ds_read_b64_tr_b16 v[254:255], v194 offset:0x3c00
	ds_read_b64_tr_b16 v[216:217], v194 offset:0x3600
	ds_read_b64_tr_b16 v[218:219], v194 offset:0x3e00
	v_cvt_pk_bf16_f32 v186, v180, v181
	v_cvt_pk_bf16_f32 v187, v220, v221
	v_exp_f32_e32 v96, v96
	v_exp_f32_e32 v97, v97
	v_mfma_f32_32x32x16_bf16 v[32:47], v[176:179], v[116:119], v[32:47]
	v_exp_f32_e32 v98, v98
	v_exp_f32_e32 v99, v99
	s_waitcnt vmcnt(3)
	ds_write_b128 v188, v[156:159]
	global_load_dwordx4 v[156:159], v247, s[98:99] offset:2048
	v_mfma_f32_32x32x16_bf16 v[0:15], v[176:179], v[248:251], v[0:15]
	v_cvt_pk_bf16_f32 v180, v96, v97
	v_cvt_pk_bf16_f32 v181, v98, v99
	v_exp_f32_e32 v100, v100
	v_exp_f32_e32 v101, v101
	v_mfma_f32_32x32x16_bf16 v[16:31], v[176:179], v[212:215], v[16:31]
	v_exp_f32_e32 v96, v102
	v_exp_f32_e32 v97, v103
	v_mfma_f32_16x16x32_bf16 v[64:67], v[176:179], v[148:151], v[64:67]
	s_waitcnt lgkmcnt(0)
	v_mfma_f32_32x32x16_bf16 v[48:63], v[172:175], v[120:123], v[48:63]
	v_cvt_pk_bf16_f32 v178, v100, v101
	v_cvt_pk_bf16_f32 v179, v96, v97
	v_exp_f32_e32 v98, v104
	v_exp_f32_e32 v99, v105
	v_mfma_f32_32x32x16_bf16 v[32:47], v[172:175], v[124:127], v[32:47]
	v_exp_f32_e32 v96, v106
	v_exp_f32_e32 v97, v107
	s_waitcnt vmcnt(3)
	ds_write_b128 v189, v[152:155]
	global_load_dwordx4 v[152:155], v247, s[100:101] offset:2048
	v_mfma_f32_32x32x16_bf16 v[0:15], v[172:175], v[252:255], v[0:15]
	v_cvt_pk_bf16_f32 v188, v98, v99
	v_cvt_pk_bf16_f32 v189, v96, v97
	v_exp_f32_e32 v100, v108
	v_exp_f32_e32 v101, v109
	v_mfma_f32_32x32x16_bf16 v[16:31], v[172:175], v[216:219], v[16:31]
	v_exp_f32_e32 v96, v110
	v_exp_f32_e32 v97, v111
	v_mfma_f32_16x16x32_bf16 v[64:67], v[172:175], v[148:151], v[64:67]
	v_cvt_pk_bf16_f32 v174, v100, v101
	v_cvt_pk_bf16_f32 v175, v96, v97
	s_add_i32 s5, s5, 1
	s_mov_b32 s9, s4
	s_mov_b32 s4, s6
	s_cmp_lg_u32 s92, s5
	s_mov_b32 s6, s8
	s_cbranch_scc1 .LBB0_105
; #define MFMA32(a, b, c) __builtin_amdgcn_mfma_f32_32x32x16_bf16(a, b, c, 0, 0, 0)
; template <bool SAFE>
; __device__ __forceinline__ void diff_core(const bf16* __restrict__ Kh, const bf16* __restrict__ Vh, const int NT, const bf16x8* qr, char* lds,
;                                           const int wid, const int lane_unused, f32x16* o, f32x16& lacc, float& l_reg) {
;     ...
;   pv_d0(o, vb0 + bp * SHM_V, pa0, pa1, pa2, pa3);
;   if constexpr (!SAFE) {
;     lacc = MFMA32(pa0, ones, lacc); lacc = MFMA32(pa1, ones, lacc); lacc = MFMA32(pa2, ones, lacc); lacc = MFMA32(pa3, ones, lacc); }
; __device__ __forceinline__ void diff_attn_item(const bf16* __restrict__ qkv, bf16* __restrict__ mix, const float* __restrict__ dg,
;                                int tok0  , int key0  , int seq, int head, float lam, float oscale, const int W) {
;     ...
;     bool bad = (FORCE_SAFE != 0);
; #pragma unroll
;     for (int r = 0; r < 16; ++r) bad = bad || !(lacc[r] < 1.0e30f);
;     if (lane == 0) flag_l[wid] = __any(bad) ? 1 : 0;
	s_waitcnt vmcnt(0)
	v_add_u32_e32 v168, s7, v211
	ds_read_b64_tr_b16 v[80:81], v168 offset:0
	ds_read_b64_tr_b16 v[82:83], v168 offset:0x800
	ds_read_b64_tr_b16 v[84:85], v168 offset:0x1000
	ds_read_b64_tr_b16 v[86:87], v168 offset:0x1800
	ds_read_b64_tr_b16 v[88:89], v168 offset:0x2000
	ds_read_b64_tr_b16 v[90:91], v168 offset:0x2800
	ds_read_b64_tr_b16 v[92:93], v168 offset:0x3000
	ds_read_b64_tr_b16 v[94:95], v168 offset:0x3800
	s_waitcnt lgkmcnt(0)
	s_waitcnt vmcnt(0)
	v_mov_b32_e32 v162, v182
	v_mov_b32_e32 v163, v183
	v_mov_b32_e32 v172, v186
	v_mov_b32_e32 v173, v187
	v_mov_b32_e32 v182, v178
	v_mov_b32_e32 v183, v179
	v_mov_b32_e32 v190, v174
	v_mov_b32_e32 v191, v175
	ds_read_b64_tr_b16 v[96:97], v168 offset:0x200
	ds_read_b64_tr_b16 v[98:99], v168 offset:0xa00
	ds_read_b64_tr_b16 v[100:101], v168 offset:0x1200
	ds_read_b64_tr_b16 v[102:103], v168 offset:0x1a00
	ds_read_b64_tr_b16 v[104:105], v168 offset:0x2200
	ds_read_b64_tr_b16 v[106:107], v168 offset:0x2a00
	ds_read_b64_tr_b16 v[108:109], v168 offset:0x3200
	ds_read_b64_tr_b16 v[110:111], v168 offset:0x3a00
	s_waitcnt lgkmcnt(0)
	ds_read_b64_tr_b16 v[112:113], v168 offset:0x400
	ds_read_b64_tr_b16 v[114:115], v168 offset:0xc00
	ds_read_b64_tr_b16 v[116:117], v168 offset:0x1400
	ds_read_b64_tr_b16 v[118:119], v168 offset:0x1c00
	ds_read_b64_tr_b16 v[120:121], v168 offset:0x2400
	ds_read_b64_tr_b16 v[122:123], v168 offset:0x2c00
	ds_read_b64_tr_b16 v[124:125], v168 offset:0x3400
	ds_read_b64_tr_b16 v[126:127], v168 offset:0x3c00
	s_waitcnt lgkmcnt(0)
	ds_read_b64_tr_b16 v[152:153], v168 offset:0x600
	ds_read_b64_tr_b16 v[154:155], v168 offset:0xe00
	ds_read_b64_tr_b16 v[156:157], v168 offset:0x1600
	ds_read_b64_tr_b16 v[158:159], v168 offset:0x1e00
	ds_read_b64_tr_b16 v[164:165], v168 offset:0x2600
	ds_read_b64_tr_b16 v[166:167], v168 offset:0x2e00
	ds_read_b64_tr_b16 v[174:175], v168 offset:0x3600
	ds_read_b64_tr_b16 v[176:177], v168 offset:0x3e00
	s_waitcnt lgkmcnt(0)
	v_mfma_f32_16x16x32_bf16 v[64:67], v[160:163], v[148:151], v[64:67]
	v_cmp_eq_u32_e32 vcc, 0, v200
	v_mfma_f32_32x32x16_bf16 v[48:63], v[160:163], v[80:83], v[48:63]
	v_mfma_f32_32x32x16_bf16 v[32:47], v[160:163], v[96:99], v[32:47]
	v_mfma_f32_32x32x16_bf16 v[0:15], v[160:163], v[112:115], v[0:15]
	v_mfma_f32_32x32x16_bf16 v[16:31], v[160:163], v[152:155], v[16:31]
	v_mfma_f32_16x16x32_bf16 v[64:67], v[170:173], v[148:151], v[64:67]
	v_mfma_f32_32x32x16_bf16 v[48:63], v[170:173], v[84:87], v[48:63]
	v_mfma_f32_32x32x16_bf16 v[32:47], v[170:173], v[100:103], v[32:47]
	v_mfma_f32_32x32x16_bf16 v[0:15], v[170:173], v[116:119], v[0:15]
	v_mfma_f32_32x32x16_bf16 v[16:31], v[170:173], v[156:159], v[16:31]
	v_mfma_f32_16x16x32_bf16 v[64:67], v[180:183], v[148:151], v[64:67]
	v_mfma_f32_32x32x16_bf16 v[48:63], v[180:183], v[88:91], v[48:63]
	v_mfma_f32_32x32x16_bf16 v[32:47], v[180:183], v[104:107], v[32:47]
	v_mfma_f32_32x32x16_bf16 v[0:15], v[180:183], v[120:123], v[0:15]
	v_mfma_f32_32x32x16_bf16 v[16:31], v[180:183], v[164:167], v[16:31]
	v_mfma_f32_16x16x32_bf16 v[64:67], v[188:191], v[148:151], v[64:67]
	v_mfma_f32_32x32x16_bf16 v[48:63], v[188:191], v[92:95], v[48:63]
	v_mfma_f32_32x32x16_bf16 v[32:47], v[188:191], v[108:111], v[32:47]
	v_mfma_f32_32x32x16_bf16 v[0:15], v[188:191], v[124:127], v[0:15]
	v_mfma_f32_32x32x16_bf16 v[16:31], v[188:191], v[174:177], v[16:31]
	v_and_b32_e32 v248, 15, v200
	v_lshrrev_b32_e32 v249, 4, v200
	v_and_b32_e32 v250, 1, v200
	v_lshlrev_b32_e32 v249, 4, v249
	v_lshl_add_u32 v249, v250, 6, v249
	v_add_u32_e32 v249, s62, v249
	v_cmp_gt_u32_e64 s[98:99], 2, v248
	v_lshl_add_u32 v250, v198, 4, s62
	s_nop 7
	s_and_saveexec_b64 s[100:101], s[98:99]
	ds_write_b128 v249, v[64:67]
	s_mov_b64 exec, s[100:101]
	s_waitcnt lgkmcnt(0)
	ds_read_b128 v[64:67], v250
	ds_read_b128 v[68:71], v250 offset:32
	ds_read_b128 v[72:75], v250 offset:64
	ds_read_b128 v[76:79], v250 offset:96
	s_waitcnt lgkmcnt(0)
	s_and_saveexec_b64 s[6:7], vcc
	s_cbranch_execz .LBB0_108
	s_nop 5
	v_cmp_ngt_f32_e32 vcc, s85, v64
	v_cmp_ngt_f32_e64 s[4:5], s85, v65
	s_or_b64 s[4:5], vcc, s[4:5]
	v_cmp_ngt_f32_e32 vcc, s85, v66
	s_or_b64 s[4:5], s[4:5], vcc
	v_cmp_ngt_f32_e32 vcc, s85, v67
	s_or_b64 s[4:5], s[4:5], vcc
	v_cmp_ngt_f32_e32 vcc, s85, v68
	s_or_b64 s[4:5], s[4:5], vcc
	v_cmp_ngt_f32_e32 vcc, s85, v69
	s_or_b64 s[4:5], s[4:5], vcc
	v_cmp_ngt_f32_e32 vcc, s85, v70
	s_or_b64 s[4:5], s[4:5], vcc
	v_cmp_ngt_f32_e32 vcc, s85, v71
	s_or_b64 s[4:5], s[4:5], vcc
	v_cmp_ngt_f32_e32 vcc, s85, v72
	s_or_b64 s[4:5], s[4:5], vcc
	v_cmp_ngt_f32_e32 vcc, s85, v73
	s_or_b64 s[4:5], s[4:5], vcc
	v_cmp_ngt_f32_e32 vcc, s85, v74
	s_or_b64 s[4:5], s[4:5], vcc
	v_cmp_ngt_f32_e32 vcc, s85, v75
	s_or_b64 s[4:5], s[4:5], vcc
	v_cmp_ngt_f32_e32 vcc, s85, v76
	s_or_b64 s[4:5], s[4:5], vcc
	v_cmp_ngt_f32_e32 vcc, s85, v77
	s_or_b64 s[4:5], s[4:5], vcc
	v_cmp_ngt_f32_e32 vcc, s85, v78
	s_or_b64 s[4:5], s[4:5], vcc
	v_cmp_ngt_f32_e32 vcc, s85, v79
	s_or_b64 s[4:5], s[4:5], vcc
	v_cndmask_b32_e64 v80, 0, 1, s[4:5]
	v_cmp_ne_u32_e32 vcc, 0, v80
	s_cmp_lg_u64 vcc, 0
	s_cselect_b64 s[4:5], -1, 0
	v_cndmask_b32_e64 v80, 0, 1, s[4:5]
	v_readlane_b32 s4, v246, 17
	s_nop 1
	v_mov_b32_e32 v81, s4
	ds_write_b32 v81, v80

; template <int KS, bool SAFE> __device__ __forceinline__ void fused_ks(f32x16* o, f32x16& lacc, int vb, const VFrag& cur, VFrag& nxt, f32x16& p0, f32x16& p1, float& ps, ...
;   if constexpr (KS < 3) { vfrag_issue<KS + 1>(nxt, vb); asm volatile("s_waitcnt lgkmcnt(8)" ::: "memory"); }
;   else asm volatile("s_waitcnt lgkmcnt(0)" ::: "memory");
;   const bf16x8 pa = (KS == 0) ? pa0 : (KS == 1) ? pa1 : (KS == 2) ? pa2 : pa3;
;   SBAR();
;   o[0] = MFMA32(pa, PKV(cur.l0, cur.h0), o[0]); SBAR(); sm1_chunk<KS * 4 + 0>(p0, p1); if constexpr (KS > 0) SM2_UNIT(2 * KS - 1); SBAR();
;   o[1] = MFMA32(pa, PKV(cur.l1, cur.h1), o[1]); SBAR(); sm1_chunk<KS * 4 + 1>(p0, p1);
;   if (dow) {
;     if constexpr (KS == 0) { asm volatile("s_waitcnt vmcnt(0)" ::: "memory"); *reinterpret_cast<bf16x8*>(sd.k0) = st.ks0; }
;     else if constexpr (KS == 1) *reinterpret_cast<bf16x8*>(sd.k1) = st.ks1;
;     else if constexpr (KS == 2) *reinterpret_cast<bf16x8*>(sd.v0) = st.vs0;
;     else *reinterpret_cast<bf16x8*>(sd.v1) = st.vs1;
;   }
;   SBAR();
;   o[2] = MFMA32(pa, PKV(cur.l2, cur.h2), o[2]); SBAR(); sm1_chunk<KS * 4 + 2>(p0, p1); SM2_UNIT(2 * KS); SBAR();
;   o[3] = MFMA32(pa, PKV(cur.l3, cur.h3), o[3]); SBAR(); sm1_chunk<KS * 4 + 3>(p0, p1); SBAR();
;   if constexpr (!SAFE) { lacc = MFMA32(pa, ones, lacc); SBAR(); }
; }
; template <bool SAFE> ...
;   bf16x8 kb[8];
; #pragma unroll
;   for (int d0 = 0; d0 < 4; ++d0) { const int cb = (cb0 + d0 * 16 + hi * 8) * 2;
;     kb[2 * d0] = *reinterpret_cast<const bf16x8*>((const char*)Ks + KSWZ(r32, cb));
;     kb[2 * d0 + 1] = *reinterpret_cast<const bf16x8*>((const char*)Ks + KSWZ(32 + r32, cb)); }
;   VFrag fa, fb;
;   vfrag_issue<0>(fa, vb);
;   p0 = MFMA32(kb[0], qr[0], cinit); p1 = MFMA32(kb[1], qr[0], cinit);
; #pragma unroll
;   for (int d0 = 1; d0 < 4; ++d0) { p0 = MFMA32(kb[2 * d0], qr[d0], p0); p1 = MFMA32(kb[2 * d0 + 1], qr[d0], p1); }
;   SBAR();
;   unsigned a0, a1, b0, b1; ps = 0.f;
;   fused_ks<0, SAFE>(o, lacc, vb, fa, fb, p0, p1, ps, a0, a1, b0, b1, pa0, pa1, pa2, pa3, st, sd, dow, ones);
;   fused_ks<1, SAFE>(o, lacc, vb, fb, fa, p0, p1, ps, a0, a1, b0, b1, pa0, pa1, pa2, pa3, st, sd, dow, ones);
;   fused_ks<2, SAFE>(o, lacc, vb, fa, fb, p0, p1, ps, a0, a1, b0, b1, pa0, pa1, pa2, pa3, st, sd, dow, ones);
;   fused_ks<3, SAFE>(o, lacc, vb, fb, fa, p0, p1, ps, a0, a1, b0, b1, pa0, pa1, pa2, pa3, st, sd, dow, ones);
.LBB0_316:
	ds_read_b128 v[212:215], v77 offset:49152
	ds_read_b128 v[216:219], v77 offset:57344
	s_lshl_b32 s11, s10, 14
	s_add_i32 s8, s11, 0
	s_add_i32 s98, s7, 2
	s_min_i32 s98, s98, s64
	s_mul_i32 s98, s98, 0x60000
	s_add_u32 s98, s14, s98
	s_addc_u32 s99, s15, 0
	s_add_u32 s100, s98, 0x30000
	s_addc_u32 s101, s99, 0
	v_add_u32_e32 v173, s8, v209
	v_mov_b32_e32 v176, v180
	v_mfma_f32_32x32x16_bf16 v[112:127], v[68:71], v[132:135], v[80:95]
	v_mov_b32_e32 v180, v160
	v_add_u32_e32 v160, s8, v210
	v_lshl_add_u32 v194, s6, 14, v211
	s_lshl_b32 s9, s27, 14
	s_add_i32 s9, s9, 0
	s_mov_b32 s26, s27
	v_add_u32_e32 v76, s9, v207
	v_mov_b32_e32 v184, v170
	v_mfma_f32_32x32x16_bf16 v[96:111], v[72:75], v[132:135], v[80:95]
	ds_read_b128 v[68:71], v173 offset:49152
	ds_read_b128 v[72:75], v173 offset:57344
	v_mov_b32_e32 v177, v181
	v_mov_b32_e32 v172, v188
	v_mov_b32_e32 v181, v161
	v_add_u32_e32 v188, s9, v205
	v_add_u32_e32 v161, s9, v203
	v_add_u32_e32 v170, s9, v204
	s_waitcnt lgkmcnt(3)
	v_mfma_f32_32x32x16_bf16 v[112:127], v[212:215], v[136:139], v[112:127]
	ds_read_b128 v[212:215], v160 offset:49152
	v_mov_b32_e32 v185, v171
	s_waitcnt lgkmcnt(3)
	v_mfma_f32_32x32x16_bf16 v[96:111], v[216:219], v[136:139], v[96:111]
	ds_read_b128 v[216:219], v160 offset:57344
	v_mov_b32_e32 v173, v189
	v_add_u32_e32 v189, s9, v206
	v_add_u32_e32 v77, s9, v208
	s_waitcnt lgkmcnt(3)
	v_mfma_f32_32x32x16_bf16 v[112:127], v[68:71], v[140:143], v[112:127]
	ds_read_b64_tr_b16 v[220:221], v194 offset:0
	ds_read_b64_tr_b16 v[222:223], v194 offset:0x800
	s_waitcnt lgkmcnt(4)
	v_mfma_f32_32x32x16_bf16 v[96:111], v[72:75], v[140:143], v[96:111]
	s_waitcnt lgkmcnt(3)
	v_mfma_f32_32x32x16_bf16 v[112:127], v[212:215], v[144:147], v[112:127]
	ds_read_b64_tr_b16 v[212:213], v194 offset:0x200
	ds_read_b64_tr_b16 v[214:215], v194 offset:0xa00
	ds_read_b64_tr_b16 v[224:225], v194 offset:0x400
	ds_read_b64_tr_b16 v[226:227], v194 offset:0xc00
	ds_read_b64_tr_b16 v[228:229], v194 offset:0x600
	ds_read_b64_tr_b16 v[230:231], v194 offset:0xe00
	s_waitcnt lgkmcnt(7)
	v_mfma_f32_32x32x16_bf16 v[96:111], v[216:219], v[144:147], v[96:111]
	ds_read_b64_tr_b16 v[216:217], v194 offset:0x1000
	ds_read_b64_tr_b16 v[218:219], v194 offset:0x1800
	ds_read_b64_tr_b16 v[232:233], v194 offset:0x1200
	ds_read_b64_tr_b16 v[234:235], v194 offset:0x1a00
	ds_read_b64_tr_b16 v[236:237], v194 offset:0x1400
	ds_read_b64_tr_b16 v[238:239], v194 offset:0x1c00
	ds_read_b64_tr_b16 v[240:241], v194 offset:0x1600
	ds_read_b64_tr_b16 v[242:243], v194 offset:0x1e00
	s_waitcnt lgkmcnt(8)
	v_mfma_f32_32x32x16_bf16 v[48:63], v[180:183], v[220:223], v[48:63]
	s_nop 0
	v_exp_f32_e32 v112, v112
	v_exp_f32_e32 v113, v113
	v_mfma_f32_32x32x16_bf16 v[32:47], v[180:183], v[212:215], v[32:47]
	v_exp_f32_e32 v114, v114
	v_exp_f32_e32 v115, v115
	s_waitcnt vmcnt(3)
	ds_write_b128 v161, v[166:169] offset:49152
	global_load_dwordx4 v[166:169], v247, s[98:99] offset:1024
	v_mfma_f32_32x32x16_bf16 v[0:15], v[180:183], v[224:227], v[0:15]
	v_exp_f32_e32 v171, v116
	v_cvt_pk_bf16_f32 v160, v112, v113
	v_cvt_pk_bf16_f32 v161, v114, v115
	v_exp_f32_e32 v220, v117
	v_mfma_f32_32x32x16_bf16 v[16:31], v[180:183], v[228:231], v[16:31]
	v_exp_f32_e32 v221, v118
	v_exp_f32_e32 v222, v119
	v_mfma_f32_16x16x32_bf16 v[64:67], v[180:183], v[148:151], v[64:67]
	ds_read_b64_tr_b16 v[112:113], v194 offset:0x2000
	ds_read_b64_tr_b16 v[114:115], v194 offset:0x2800
	ds_read_b64_tr_b16 v[116:117], v194 offset:0x2200
	ds_read_b64_tr_b16 v[118:119], v194 offset:0x2a00
	ds_read_b64_tr_b16 v[248:249], v194 offset:0x2400
	ds_read_b64_tr_b16 v[250:251], v194 offset:0x2c00
	ds_read_b64_tr_b16 v[212:213], v194 offset:0x2600
	ds_read_b64_tr_b16 v[214:215], v194 offset:0x2e00
	s_waitcnt lgkmcnt(8)
	v_mfma_f32_32x32x16_bf16 v[48:63], v[184:187], v[216:219], v[48:63]
	v_cvt_pk_bf16_f32 v182, v171, v220
	v_cvt_pk_bf16_f32 v183, v221, v222
	v_exp_f32_e32 v120, v120
	v_exp_f32_e32 v121, v121
	v_mfma_f32_32x32x16_bf16 v[32:47], v[184:187], v[232:235], v[32:47]
	v_exp_f32_e32 v122, v122
	v_exp_f32_e32 v123, v123
	s_waitcnt vmcnt(3)
	ds_write_b128 v170, v[162:165] offset:49152
	global_load_dwordx4 v[162:165], v247, s[100:101] offset:1024
	v_mfma_f32_32x32x16_bf16 v[0:15], v[184:187], v[236:239], v[0:15]
	v_exp_f32_e32 v180, v124
	v_exp_f32_e32 v181, v125
	v_cvt_pk_bf16_f32 v170, v120, v121
	v_cvt_pk_bf16_f32 v171, v122, v123
	v_mfma_f32_32x32x16_bf16 v[16:31], v[184:187], v[240:243], v[16:31]
	v_exp_f32_e32 v220, v126
	v_exp_f32_e32 v221, v127
	v_mfma_f32_16x16x32_bf16 v[64:67], v[184:187], v[148:151], v[64:67]
	s_waitcnt lgkmcnt(0)
	s_barrier
; #define SBAR() __builtin_amdgcn_sched_barrier(0)
; template <int KS, bool SAFE> __device__ __forceinline__ void fused_ks(f32x16* o, f32x16& lacc, int vb, const VFrag& cur, VFrag& nxt, f32x16& p0, f32x16& p1, float& ps, ...
;   if constexpr (KS < 3) { vfrag_issue<KS + 1>(nxt, vb); asm volatile("s_waitcnt lgkmcnt(8)" ::: "memory"); }
;   else asm volatile("s_waitcnt lgkmcnt(0)" ::: "memory");
;   const bf16x8 pa = (KS == 0) ? pa0 : (KS == 1) ? pa1 : (KS == 2) ? pa2 : pa3;
;   SBAR();
;   o[0] = MFMA32(pa, PKV(cur.l0, cur.h0), o[0]); SBAR(); sm1_chunk<KS * 4 + 0>(p0, p1); if constexpr (KS > 0) SM2_UNIT(2 * KS - 1); SBAR();
;   o[1] = MFMA32(pa, PKV(cur.l1, cur.h1), o[1]); SBAR(); sm1_chunk<KS * 4 + 1>(p0, p1);
;   if (dow) {
;     if constexpr (KS == 0) { asm volatile("s_waitcnt vmcnt(0)" ::: "memory"); *reinterpret_cast<bf16x8*>(sd.k0) = st.ks0; }
;     else if constexpr (KS == 1) *reinterpret_cast<bf16x8*>(sd.k1) = st.ks1;
;     else if constexpr (KS == 2) *reinterpret_cast<bf16x8*>(sd.v0) = st.vs0;
;     else *reinterpret_cast<bf16x8*>(sd.v1) = st.vs1;
;   }
;   SBAR();
;   o[2] = MFMA32(pa, PKV(cur.l2, cur.h2), o[2]); SBAR(); sm1_chunk<KS * 4 + 2>(p0, p1); SM2_UNIT(2 * KS); SBAR();
;   o[3] = MFMA32(pa, PKV(cur.l3, cur.h3), o[3]); SBAR(); sm1_chunk<KS * 4 + 3>(p0, p1); SBAR();
;   if constexpr (!SAFE) { lacc = MFMA32(pa, ones, lacc); SBAR(); }
; }
; template <bool SAFE>
; __device__ __forceinline__ void diff_core(const bf16* __restrict__ Kh, const bf16* __restrict__ Vh, const int NT, const bf16x8* qr, char* lds,
;                                           const int wid, const int lane_unused, f32x16* o, f32x16& lacc, float& l_reg) {
;     ...
;   for (int j = 1; j < NT; ++j) {
;     const bool dow = true;
;     const bf16* Kc = (const bf16*)((const char*)K_lds + bc * SHM_K);
;     StgDst sd;
;     sd.v0 = (char*)V_lds + bn * SHM_V + vst0; sd.v1 = (char*)V_lds + bn * SHM_V + vst1;
;     sd.k0 = (char*)K_lds + bn * SHM_K + kw0;  sd.k1 = (char*)K_lds + bn * SHM_K + kw1;
;     tile_step<SAFE>(o, lacc, Kc, vb0 + bp * SHM_V, qr, rk, hi, cb0, p0, p1, cinit, ps, pa0, pa1, pa2, pa3, sr_[0], sd, dow, ones);
;     SLOAD(0, min(j + 2, NT - 1) * 64);
;     SBAR();
;     if constexpr (SAFE) FIXUP(Kc, false);
;     asm volatile("s_waitcnt lgkmcnt(0)" ::: "memory"); __builtin_amdgcn_s_barrier(); asm volatile("" ::: "memory");
;     const int t_ = bp; bp = bc; bc = bn; bn = t_;
	v_mfma_f32_32x32x16_bf16 v[48:63], v[176:179], v[112:115], v[48:63]
	ds_read_b128 v[68:71], v76 offset:49152
	ds_read_b128 v[72:75], v76 offset:57344
	ds_read_b64_tr_b16 v[120:121], v194 offset:0x3000
	ds_read_b64_tr_b16 v[122:123], v194 offset:0x3800
	ds_read_b64_tr_b16 v[124:125], v194 offset:0x3200
	ds_read_b64_tr_b16 v[126:127], v194 offset:0x3a00
	ds_read_b64_tr_b16 v[252:253], v194 offset:0x3400
	ds_read_b64_tr_b16 v[254:255], v194 offset:0x3c00
	ds_read_b64_tr_b16 v[216:217], v194 offset:0x3600
	ds_read_b64_tr_b16 v[218:219], v194 offset:0x3e00
	v_cvt_pk_bf16_f32 v186, v180, v181
	v_cvt_pk_bf16_f32 v187, v220, v221
	v_exp_f32_e32 v96, v96
	v_exp_f32_e32 v97, v97
	v_mfma_f32_32x32x16_bf16 v[32:47], v[176:179], v[116:119], v[32:47]
	v_exp_f32_e32 v98, v98
	v_exp_f32_e32 v99, v99
	s_waitcnt vmcnt(3)
	ds_write_b128 v188, v[156:159]
	global_load_dwordx4 v[156:159], v247, s[98:99] offset:2048
	v_mfma_f32_32x32x16_bf16 v[0:15], v[176:179], v[248:251], v[0:15]
	v_cvt_pk_bf16_f32 v180, v96, v97
	v_cvt_pk_bf16_f32 v181, v98, v99
	v_exp_f32_e32 v100, v100
	v_exp_f32_e32 v101, v101
	v_mfma_f32_32x32x16_bf16 v[16:31], v[176:179], v[212:215], v[16:31]
	v_exp_f32_e32 v96, v102
	v_exp_f32_e32 v97, v103
	v_mfma_f32_16x16x32_bf16 v[64:67], v[176:179], v[148:151], v[64:67]
	s_waitcnt lgkmcnt(0)
	v_mfma_f32_32x32x16_bf16 v[48:63], v[172:175], v[120:123], v[48:63]
	v_cvt_pk_bf16_f32 v178, v100, v101
	v_cvt_pk_bf16_f32 v179, v96, v97
	v_exp_f32_e32 v98, v104
	v_exp_f32_e32 v99, v105
	v_mfma_f32_32x32x16_bf16 v[32:47], v[172:175], v[124:127], v[32:47]
	v_exp_f32_e32 v96, v106
	v_exp_f32_e32 v97, v107
	s_waitcnt vmcnt(3)
	ds_write_b128 v189, v[152:155]
	global_load_dwordx4 v[152:155], v247, s[100:101] offset:2048
	v_mfma_f32_32x32x16_bf16 v[0:15], v[172:175], v[252:255], v[0:15]
	v_cvt_pk_bf16_f32 v188, v98, v99
	v_cvt_pk_bf16_f32 v189, v96, v97
	v_exp_f32_e32 v100, v108
	v_exp_f32_e32 v101, v109
	v_mfma_f32_32x32x16_bf16 v[16:31], v[172:175], v[216:219], v[16:31]
	v_exp_f32_e32 v96, v110
	v_exp_f32_e32 v97, v111
	v_mfma_f32_16x16x32_bf16 v[64:67], v[172:175], v[148:151], v[64:67]
	v_cvt_pk_bf16_f32 v174, v100, v101
	v_cvt_pk_bf16_f32 v175, v96, v97
	s_add_i32 s7, s7, 1
	s_mov_b32 s27, s6
	s_mov_b32 s6, s10
	s_cmp_lg_u32 s55, s7
	s_mov_b32 s10, s26
	s_cbranch_scc1 .LBB0_316
; #define MFMA32(a, b, c) __builtin_amdgcn_mfma_f32_32x32x16_bf16(a, b, c, 0, 0, 0)
; template <bool SAFE>
; __device__ __forceinline__ void diff_core(const bf16* __restrict__ Kh, const bf16* __restrict__ Vh, const int NT, const bf16x8* qr, char* lds,
;                                           const int wid, const int lane_unused, f32x16* o, f32x16& lacc, float& l_reg) {
;     ...
;   pv_d0(o, vb0 + bp * SHM_V, pa0, pa1, pa2, pa3);
;   if constexpr (!SAFE) {
;     lacc = MFMA32(pa0, ones, lacc); lacc = MFMA32(pa1, ones, lacc); lacc = MFMA32(pa2, ones, lacc); lacc = MFMA32(pa3, ones, lacc); }
; __device__ __forceinline__ void diff_attn_item(const bf16* __restrict__ qkv, bf16* __restrict__ mix, const float* __restrict__ dg,
;                                int tok0  , int key0  , int seq, int head, float lam, float oscale, const int W) {
;     ...
;     bool bad = (FORCE_SAFE != 0);
; #pragma unroll
;     for (int r = 0; r < 16; ++r) bad = bad || !(lacc[r] < 1.0e30f);
;     if (lane == 0) flag_l[wid] = __any(bad) ? 1 : 0;
	s_waitcnt vmcnt(0)
	v_add_u32_e32 v168, s11, v211
	ds_read_b64_tr_b16 v[80:81], v168 offset:0
	ds_read_b64_tr_b16 v[82:83], v168 offset:0x800
	ds_read_b64_tr_b16 v[84:85], v168 offset:0x1000
	ds_read_b64_tr_b16 v[86:87], v168 offset:0x1800
	ds_read_b64_tr_b16 v[88:89], v168 offset:0x2000
	ds_read_b64_tr_b16 v[90:91], v168 offset:0x2800
	ds_read_b64_tr_b16 v[92:93], v168 offset:0x3000
	ds_read_b64_tr_b16 v[94:95], v168 offset:0x3800
	s_waitcnt lgkmcnt(0)
	s_waitcnt vmcnt(0)
	v_mov_b32_e32 v162, v182
	v_mov_b32_e32 v163, v183
	v_mov_b32_e32 v172, v186
	v_mov_b32_e32 v173, v187
	v_mov_b32_e32 v182, v178
	v_mov_b32_e32 v183, v179
	v_mov_b32_e32 v190, v174
	v_mov_b32_e32 v191, v175
	ds_read_b64_tr_b16 v[96:97], v168 offset:0x200
	ds_read_b64_tr_b16 v[98:99], v168 offset:0xa00
	ds_read_b64_tr_b16 v[100:101], v168 offset:0x1200
	ds_read_b64_tr_b16 v[102:103], v168 offset:0x1a00
	ds_read_b64_tr_b16 v[104:105], v168 offset:0x2200
	ds_read_b64_tr_b16 v[106:107], v168 offset:0x2a00
	ds_read_b64_tr_b16 v[108:109], v168 offset:0x3200
	ds_read_b64_tr_b16 v[110:111], v168 offset:0x3a00
	s_waitcnt lgkmcnt(0)
	ds_read_b64_tr_b16 v[112:113], v168 offset:0x400
	ds_read_b64_tr_b16 v[114:115], v168 offset:0xc00
	ds_read_b64_tr_b16 v[116:117], v168 offset:0x1400
	ds_read_b64_tr_b16 v[118:119], v168 offset:0x1c00
	ds_read_b64_tr_b16 v[120:121], v168 offset:0x2400
	ds_read_b64_tr_b16 v[122:123], v168 offset:0x2c00
	ds_read_b64_tr_b16 v[124:125], v168 offset:0x3400
	ds_read_b64_tr_b16 v[126:127], v168 offset:0x3c00
	s_waitcnt lgkmcnt(0)
	ds_read_b64_tr_b16 v[152:153], v168 offset:0x600
	ds_read_b64_tr_b16 v[154:155], v168 offset:0xe00
	ds_read_b64_tr_b16 v[156:157], v168 offset:0x1600
	ds_read_b64_tr_b16 v[158:159], v168 offset:0x1e00
	ds_read_b64_tr_b16 v[164:165], v168 offset:0x2600
	ds_read_b64_tr_b16 v[166:167], v168 offset:0x2e00
	ds_read_b64_tr_b16 v[174:175], v168 offset:0x3600
	ds_read_b64_tr_b16 v[176:177], v168 offset:0x3e00
	s_waitcnt lgkmcnt(0)
	v_mfma_f32_16x16x32_bf16 v[64:67], v[160:163], v[148:151], v[64:67]
	v_cmp_eq_u32_e32 vcc, 0, v200
	v_mfma_f32_32x32x16_bf16 v[48:63], v[160:163], v[80:83], v[48:63]
	v_mfma_f32_32x32x16_bf16 v[32:47], v[160:163], v[96:99], v[32:47]
	v_mfma_f32_32x32x16_bf16 v[0:15], v[160:163], v[112:115], v[0:15]
	v_mfma_f32_32x32x16_bf16 v[16:31], v[160:163], v[152:155], v[16:31]
	v_mfma_f32_16x16x32_bf16 v[64:67], v[170:173], v[148:151], v[64:67]
	v_mfma_f32_32x32x16_bf16 v[48:63], v[170:173], v[84:87], v[48:63]
	v_mfma_f32_32x32x16_bf16 v[32:47], v[170:173], v[100:103], v[32:47]
	v_mfma_f32_32x32x16_bf16 v[0:15], v[170:173], v[116:119], v[0:15]
	v_mfma_f32_32x32x16_bf16 v[16:31], v[170:173], v[156:159], v[16:31]
	v_mfma_f32_16x16x32_bf16 v[64:67], v[180:183], v[148:151], v[64:67]
	v_mfma_f32_32x32x16_bf16 v[48:63], v[180:183], v[88:91], v[48:63]
	v_mfma_f32_32x32x16_bf16 v[32:47], v[180:183], v[104:107], v[32:47]
	v_mfma_f32_32x32x16_bf16 v[0:15], v[180:183], v[120:123], v[0:15]
	v_mfma_f32_32x32x16_bf16 v[16:31], v[180:183], v[164:167], v[16:31]
	v_mfma_f32_16x16x32_bf16 v[64:67], v[188:191], v[148:151], v[64:67]
	v_mfma_f32_32x32x16_bf16 v[48:63], v[188:191], v[92:95], v[48:63]
	v_mfma_f32_32x32x16_bf16 v[32:47], v[188:191], v[108:111], v[32:47]
	v_mfma_f32_32x32x16_bf16 v[0:15], v[188:191], v[124:127], v[0:15]
	v_mfma_f32_32x32x16_bf16 v[16:31], v[188:191], v[174:177], v[16:31]
	v_and_b32_e32 v248, 15, v200
	v_lshrrev_b32_e32 v249, 4, v200
	v_and_b32_e32 v250, 1, v200
	v_lshlrev_b32_e32 v249, 4, v249
	v_lshl_add_u32 v249, v250, 6, v249
	v_add_u32_e32 v249, s62, v249
	v_cmp_gt_u32_e64 s[98:99], 2, v248
	v_lshl_add_u32 v250, v198, 4, s62
	s_nop 7
	s_and_saveexec_b64 s[100:101], s[98:99]
	ds_write_b128 v249, v[64:67]
	s_mov_b64 exec, s[100:101]
	s_waitcnt lgkmcnt(0)
	ds_read_b128 v[64:67], v250
	ds_read_b128 v[68:71], v250 offset:32
	ds_read_b128 v[72:75], v250 offset:64
	ds_read_b128 v[76:79], v250 offset:96
	s_waitcnt lgkmcnt(0)
	s_and_saveexec_b64 s[10:11], vcc
	s_cbranch_execz .LBB0_319
	s_nop 5
	v_cmp_ngt_f32_e32 vcc, s44, v64
	v_cmp_ngt_f32_e64 s[6:7], s44, v65
	s_or_b64 s[6:7], vcc, s[6:7]
	v_cmp_ngt_f32_e32 vcc, s44, v66
	s_or_b64 s[6:7], s[6:7], vcc
	v_cmp_ngt_f32_e32 vcc, s44, v67
	s_or_b64 s[6:7], s[6:7], vcc
	v_cmp_ngt_f32_e32 vcc, s44, v68
	s_or_b64 s[6:7], s[6:7], vcc
	v_cmp_ngt_f32_e32 vcc, s44, v69
	s_or_b64 s[6:7], s[6:7], vcc
	v_cmp_ngt_f32_e32 vcc, s44, v70
	s_or_b64 s[6:7], s[6:7], vcc
	v_cmp_ngt_f32_e32 vcc, s44, v71
	s_or_b64 s[6:7], s[6:7], vcc
	v_cmp_ngt_f32_e32 vcc, s44, v72
	s_or_b64 s[6:7], s[6:7], vcc
	v_cmp_ngt_f32_e32 vcc, s44, v73
	s_or_b64 s[6:7], s[6:7], vcc
	v_cmp_ngt_f32_e32 vcc, s44, v74
	s_or_b64 s[6:7], s[6:7], vcc
	v_cmp_ngt_f32_e32 vcc, s44, v75
	s_or_b64 s[6:7], s[6:7], vcc
	v_cmp_ngt_f32_e32 vcc, s44, v76
	s_or_b64 s[6:7], s[6:7], vcc
	v_cmp_ngt_f32_e32 vcc, s44, v77
	s_or_b64 s[6:7], s[6:7], vcc
	v_cmp_ngt_f32_e32 vcc, s44, v78
	s_or_b64 s[6:7], s[6:7], vcc
	v_cmp_ngt_f32_e32 vcc, s44, v79
	s_or_b64 s[6:7], s[6:7], vcc
	v_cndmask_b32_e64 v80, 0, 1, s[6:7]
	v_cmp_ne_u32_e32 vcc, 0, v80
	s_cmp_lg_u64 vcc, 0
	s_cselect_b64 s[6:7], -1, 0
	v_cndmask_b32_e64 v80, 0, 1, s[6:7]
	v_readlane_b32 s6, v246, 17
	s_nop 1
	v_mov_b32_e32 v81, s6
	ds_write_b32 v81, v80
